# grid barrier: L1 invalidate issued at arrival (the CU only polls with L1-bypassing loads until release) so its ack is off the release path; leader no longer waits for the flag atomic ack
# speedup vs baseline: 1.0097x; 1.0080x over previous
; __device__ __forceinline__ unsigned xb_ld(unsigned* p)              { return __hip_atomic_load(p, __ATOMIC_RELAXED, __HIP_MEMORY_SCOPE_AGENT); }
; __device__ __forceinline__ unsigned xb_add(unsigned* p, unsigned v) { return __hip_atomic_fetch_add(p, v, __ATOMIC_RELAXED, __HIP_MEMORY_SCOPE_AGENT); }
; #define XB_SPIN(cond, bar) do { unsigned _sp = 0; while (cond) { __builtin_amdgcn_s_sleep(1); \
;     if ((++_sp & 255u) == 0u) { if (xb_ld(&(bar)[XB_TMO])) break; if (_sp > XB_SPIN_CAP) { atomicAdd(&(bar)[XB_TMO], 1u); break; } } } } while (0)
; __device__ __forceinline__ void xcd_barrier(const XcdBarrier& b) {
;     ...
;         unsigned nloc = b.st[0], nx = b.st[1];
;         if (nloc == 0u) { xcd_barrier_complete(bar, b.x, nloc, nx); b.st[0] = nloc; b.st[1] = nx; }
;         const unsigned old = xb_add(&bar[XB_XSUB(b.x)], 1u);
;         const unsigned gen = old / nloc;
;         if (old + 1u == (gen + 1u) * nloc) {
;             __builtin_amdgcn_fence(__ATOMIC_RELEASE, "agent");
;             asm volatile("s_waitcnt vmcnt(0)" ::: "memory");
;             const unsigned og = xb_add(&bar[XB_TOP], 1u);
;             const unsigned tg = og / nx;
;             if (og + 1u == (tg + 1u) * nx) xb_add(&bar[XB_TOPGEN], 1u);
;             else XB_SPIN(xb_ld(&bar[XB_TOPGEN]) == tg, bar);
;             __builtin_amdgcn_fence(__ATOMIC_ACQUIRE, "agent");
;             xb_add(&bar[XB_XGEN(b.x)], 1u);
;             asm volatile("s_waitcnt vmcnt(0)" ::: "memory");
;         } else {
;             XB_SPIN(xb_ld(&bar[XB_XGEN(b.x)]) == gen, bar);
;             __builtin_amdgcn_fence(__ATOMIC_ACQUIRE, "agent");
.LBB0_36:
	s_or_b64 exec, exec, s[10:11]
	v_cvt_f32_u32_e32 v10, v4
	s_waitcnt vmcnt(0)
	v_readfirstlane_b32 s2, v5
	buffer_inv sc1
	v_sub_u32_e32 v5, 0, v4
	v_rcp_iflag_f32_e32 v10, v10
	v_add_u32_e32 v11, s2, v1
	v_mul_f32_e32 v10, 0x4f7ffffe, v10
	v_cvt_u32_f32_e32 v10, v10
	v_mul_lo_u32 v1, v5, v10
	v_mul_hi_u32 v1, v10, v1
	v_add_u32_e32 v1, v10, v1
	v_mul_hi_u32 v1, v11, v1
	v_mul_lo_u32 v5, v1, v4
	v_sub_u32_e32 v5, v11, v5
	v_add_u32_e32 v10, 1, v1
	v_cmp_ge_u32_e32 vcc, v5, v4
	s_nop 1
	v_cndmask_b32_e32 v1, v1, v10, vcc
	v_sub_u32_e32 v10, v5, v4
	v_cndmask_b32_e32 v5, v5, v10, vcc
	v_add_u32_e32 v10, 1, v1
	v_cmp_ge_u32_e32 vcc, v5, v4
	v_add_u32_e32 v5, 1, v11
	s_nop 0
	v_cndmask_b32_e32 v1, v1, v10, vcc
	v_mul_lo_u32 v10, v4, v1
	v_add_u32_e32 v4, v10, v4
	v_cmp_ne_u32_e32 vcc, v5, v4
	s_and_saveexec_b64 s[2:3], vcc
	s_xor_b64 s[8:9], exec, s[2:3]
	s_cbranch_execz .LBB0_50
	s_waitcnt lgkmcnt(0)
	global_load_dword v2, v252, s[6:7] offset:1024 sc1
	s_add_u32 s12, s6, 0x2400
	s_addc_u32 s13, s7, 0
	s_waitcnt vmcnt(0)
	v_cmp_eq_u32_e32 vcc, v2, v1
	s_and_saveexec_b64 s[10:11], vcc
	s_cbranch_execz .LBB0_49
	s_mov_b32 s2, 1
	s_mov_b64 s[14:15], 0
	s_branch .LBB0_40

; __device__ __forceinline__ unsigned xb_ld(unsigned* p)              { return __hip_atomic_load(p, __ATOMIC_RELAXED, __HIP_MEMORY_SCOPE_AGENT); }
; __device__ __forceinline__ unsigned xb_add(unsigned* p, unsigned v) { return __hip_atomic_fetch_add(p, v, __ATOMIC_RELAXED, __HIP_MEMORY_SCOPE_AGENT); }
; #define XB_SPIN(cond, bar) do { unsigned _sp = 0; while (cond) { __builtin_amdgcn_s_sleep(1); \
;     if ((++_sp & 255u) == 0u) { if (xb_ld(&(bar)[XB_TMO])) break; if (_sp > XB_SPIN_CAP) { atomicAdd(&(bar)[XB_TMO], 1u); break; } } } } while (0)
; __device__ __forceinline__ void xcd_barrier(const XcdBarrier& b) {
;     ...
;         if (old + 1u == (gen + 1u) * nloc) {
;             __builtin_amdgcn_fence(__ATOMIC_RELEASE, "agent");
;             asm volatile("s_waitcnt vmcnt(0)" ::: "memory");
;             const unsigned og = xb_add(&bar[XB_TOP], 1u);
;     ...
;         } else {
;             XB_SPIN(xb_ld(&bar[XB_XGEN(b.x)]) == gen, bar);
;             __builtin_amdgcn_fence(__ATOMIC_ACQUIRE, "agent");
;             asm volatile("s_waitcnt vmcnt(0)" ::: "memory");
.LBB0_49:
	s_or_b64 exec, exec, s[10:11]
	s_waitcnt vmcnt(0)
.LBB0_50:
	s_andn2_saveexec_b64 s[2:3], s[8:9]
	s_cbranch_execz .LBB0_70
	s_mov_b64 s[8:9], exec
	buffer_wbl2 sc1
	s_waitcnt lgkmcnt(0)
	s_waitcnt vmcnt(0)
	v_mbcnt_lo_u32_b32 v1, s8, 0
	v_mbcnt_hi_u32_b32 v1, s9, v1
	v_cmp_eq_u32_e32 vcc, 0, v1
	s_and_saveexec_b64 s[10:11], vcc
	s_cbranch_execz .LBB0_53
	s_bcnt1_i32_b64 s2, s[8:9]
	v_mov_b32_e32 v4, s2
	v_readlane_b32 s2, v253, 50
	v_readlane_b32 s3, v253, 51
	s_nop 4
	global_atomic_add v4, v3, v4, s[2:3] sc0

; __device__ __forceinline__ unsigned xb_ld(unsigned* p)              { return __hip_atomic_load(p, __ATOMIC_RELAXED, __HIP_MEMORY_SCOPE_AGENT); }
; __device__ __forceinline__ unsigned xb_add(unsigned* p, unsigned v) { return __hip_atomic_fetch_add(p, v, __ATOMIC_RELAXED, __HIP_MEMORY_SCOPE_AGENT); }
; #define XB_SPIN(cond, bar) do { unsigned _sp = 0; while (cond) { __builtin_amdgcn_s_sleep(1); \
;     if ((++_sp & 255u) == 0u) { if (xb_ld(&(bar)[XB_TMO])) break; if (_sp > XB_SPIN_CAP) { atomicAdd(&(bar)[XB_TMO], 1u); break; } } } } while (0)
; __device__ __forceinline__ void xcd_barrier(const XcdBarrier& b) {
;     ...
;             if (og + 1u == (tg + 1u) * nx) xb_add(&bar[XB_TOPGEN], 1u);
;             else XB_SPIN(xb_ld(&bar[XB_TOPGEN]) == tg, bar);
;             __builtin_amdgcn_fence(__ATOMIC_ACQUIRE, "agent");
;             xb_add(&bar[XB_XGEN(b.x)], 1u);
;             asm volatile("s_waitcnt vmcnt(0)" ::: "memory");
;     ...
;     __syncthreads();
.LBB0_67:
	s_or_b64 exec, exec, s[8:9]
	s_mov_b64 s[8:9], exec
	v_mbcnt_lo_u32_b32 v1, s8, 0
	v_mbcnt_hi_u32_b32 v1, s9, v1
	v_cmp_eq_u32_e32 vcc, 0, v1
	s_waitcnt vmcnt(0)
	s_and_saveexec_b64 s[10:11], vcc
	s_cbranch_execz .LBB0_69
	s_bcnt1_i32_b64 s2, s[8:9]
	v_mov_b32_e32 v1, s2
	global_atomic_add v252, v1, s[6:7] offset:1024
.LBB0_69:
	s_or_b64 exec, exec, s[10:11]
.LBB0_70:
	s_or_b64 exec, exec, s[4:5]
	s_waitcnt lgkmcnt(0)
	s_barrier
